# attention item preamble: second half of the first K tile loaded together with the other first-tile loads (one exposed memory latency less per item)
# speedup vs baseline: 1.0015x; 1.0015x over previous
; DEV void attn_item(const Params& p, int item, char* smem) {
;     ...
;   const int ntile = nkeys >> 5;
;   __syncthreads();
;   rk0 = *(const u32x4*)(Kb + (size_t)k0row * 96 + k0cc * 8);
;   rk1 = *(const u32x4*)(Kb + (size_t)k1row * 96 + k1cc * 8);
;   rv0 = *(const u32x4*)(Vb + (size_t)vrow * 8448 + vcc * 8);
;   *(u32x4*)(Ks + k0row * ASTR + k0cc * 8) = rk0;
;   if (has_k1) *(u32x4*)(Ks + k1row * ASTR + k1cc * 8) = rk1;
;   *(uint2*)(Vs + vrow * VSTR + vcc * 8) = make_uint2(rv0[0], rv0[1]);
;   *(uint2*)(Vs + vrow * VSTR + vcc * 8 + 4) = make_uint2(rv0[2], rv0[3]);
.LBB0_749:
	v_bfe_u32 v10, v172, 5, 1
	v_lshlrev_b32_e32 v0, 4, v10
	s_mul_i32 s8, s11, 0x18c000
	s_mul_hi_u32 s9, s10, 0x18c000
	v_and_b32_e32 v4, 0xffffffdf, v172
	v_lshl_add_u64 v[2:3], s[14:15], 0, v[0:1]
	s_movk_i32 s37, 0xc0
	s_add_i32 s9, s9, s8
	s_mul_i32 s8, s10, 0x18c000
	v_mad_i64_i32 v[4:5], s[14:15], v4, s37, v[2:3]
	s_add_u32 s12, s20, s8
	s_mul_i32 s11, s11, 0x108000
	s_mul_hi_u32 s34, s10, 0x108000
	global_load_dwordx4 v[156:159], v[4:5], off
	global_load_dwordx4 v[152:155], v[4:5], off offset:32
	global_load_dwordx4 v[148:151], v[4:5], off offset:64
	global_load_dwordx4 v[144:147], v[4:5], off offset:96
	global_load_dwordx4 v[140:143], v[4:5], off offset:128
	global_load_dwordx4 v[136:139], v[4:5], off offset:160
	v_or_b32_e32 v4, 32, v172
	s_addc_u32 s13, s21, s9
	s_add_i32 s11, s34, s11
	v_mad_i64_i32 v[2:3], s[14:15], v4, s37, v[2:3]
	s_mov_b32 s34, 0x2aaaaaab
	global_load_dwordx4 v[132:135], v[2:3], off
	global_load_dwordx4 v[128:131], v[2:3], off offset:32
	global_load_dwordx4 v[112:115], v[2:3], off offset:64
	global_load_dwordx4 v[116:119], v[2:3], off offset:96
	global_load_dwordx4 v[120:123], v[2:3], off offset:128
	global_load_dwordx4 v[124:127], v[2:3], off offset:160
	v_mul_hi_i32 v2, v172, s34
	v_lshrrev_b32_e32 v3, 31, v2
	v_ashrrev_i32_e32 v2, 1, v2
	v_add_u32_e32 v11, v2, v3
	v_mad_u64_u32 v[20:21], s[34:35], v11, -12, v[172:173]
	s_mul_i32 s10, s10, 0x108000
	v_mov_b64_e32 v[2:3], s[12:13]
	v_lshlrev_b32_e32 v176, 3, v20
	s_add_u32 s14, s22, s10
	v_mad_i64_i32 v[2:3], s[34:35], v11, s37, v[2:3]
	v_ashrrev_i32_e32 v177, 31, v176
	s_addc_u32 s15, s23, s11
	v_lshl_add_u64 v[2:3], v[176:177], 1, v[2:3]
	v_lshlrev_b32_e32 v4, 3, v172
	v_ashrrev_i32_e32 v12, 2, v172
	s_waitcnt lgkmcnt(0)
	s_barrier
	global_load_dwordx4 v[16:19], v[2:3], off
	v_mov_b64_e32 v[2:3], s[14:15]
	s_movk_i32 s14, 0x4200
	s_waitcnt vmcnt(35)
	v_and_b32_e32 v14, 24, v4
	v_mad_i64_i32 v[2:3], s[14:15], v12, s14, v[2:3]
	v_lshlrev_b32_e32 v4, 1, v14
	v_mov_b32_e32 v5, v1
	v_lshl_add_u64 v[6:7], v[2:3], 0, v[4:5]
	global_load_dwordx4 v[2:5], v[6:7], off
	v_and_b32_e32 v8, 0x7f, v172
	v_or_b32_e32 v13, 0x100, v8
	s_movk_i32 s14, 0x80
	v_mul_u32_u24_e32 v15, 0x1556, v13
	v_cmp_gt_i32_e64 s[38:39], s14, v172
	s_movk_i32 s14, 0x60
	v_mul_i32_i24_sdwa v21, v15, v226 dst_sel:DWORD dst_unused:UNUSED_PAD src0_sel:WORD_1 src1_sel:DWORD
	v_mul_u32_u24_sdwa v8, v15, s14 dst_sel:DWORD dst_unused:UNUSED_PAD src0_sel:WORD_1 src1_sel:DWORD
	s_movk_i32 s14, 0x68
	v_lshlrev_b32_e32 v8, 1, v8
	v_mov_b32_e32 v9, v1
	v_add_lshl_u32 v174, v21, v13, 3
	v_mul_lo_u32 v191, v11, s14
	v_lshlrev_b32_e32 v20, 4, v20
	s_movk_i32 s14, 0xd0
	v_lshl_add_u64 v[8:9], s[12:13], 0, v[8:9]
	v_ashrrev_i32_e32 v175, 31, v174
	v_lshl_add_u32 v20, v191, 1, v20
	v_mul_u32_u24_sdwa v188, v15, s14 dst_sel:DWORD dst_unused:UNUSED_PAD src0_sel:WORD_1 src1_sel:DWORD
	s_and_saveexec_b64 s[14:15], s[38:39]
	v_lshl_add_u64 v[168:169], v[174:175], 1, v[8:9]
	global_load_dwordx4 v[168:171], v[168:169], off
	s_or_b64 exec, exec, s[14:15]
	s_waitcnt vmcnt(2)
	ds_write_b128 v20, v[16:19]
	s_and_saveexec_b64 s[14:15], s[38:39]
	s_cbranch_execz .LBB0_751
	v_lshl_add_u32 v15, v174, 1, v188
	s_waitcnt vmcnt(0)
	ds_write_b128 v15, v[168:171]
